# v031 + NA: odd-step DMA issued in even step, K/V fragment reads clustered, prologue bias/mask unguarded+cndmask
# speedup vs baseline: 1.0042x; 1.0042x over previous
; #define A_DMAV(t, slot) do { const unsigned tt_ = (unsigned)((t) < NT ? (t) : NT - 1); \
;         glds16(dv_src[0] + (size_t)tt_ * 128u, (unsigned)__builtin_amdgcn_readfirstlane(lds_u + A_V0 + (slot) * A_VB + wid * 1024)); \
;         if (wid == 0) glds16(dv_src[1] + (size_t)tt_ * 128u, (unsigned)__builtin_amdgcn_readfirstlane(lds_u + A_V0 + (slot) * A_VB + 8 * 1024)); } while (0)
; template <bool NA>
; __device__ __forceinline__ void attn_unit(LAS unsigned char* lds, const bf16_t* Q, const bf16_t* Kg, const bf16_t* Kr, const bf16_t* Vt, bf16_t* O,
;                                           int h, int seqrow0, int q0, int t0, int NT, int rows, int g0, const float* rpb_h, int wid) {
;     ...
;     { A_DMAK(0, 0); A_DMAV(0, 0); A_DMAK(1, 1); A_DMAK(2, 2); A_DMAV(1, 1); }
;     asm volatile("s_waitcnt vmcnt(0)" ::: "memory");
;     __syncthreads();
;     f32x16 sA0, sA1, sB0, sB1; float tmA, tmB;
;     A_QK(sA0, sA1, 0);
;     A_MASK(sA0, sA1, 0);
;     tmA = rowmax32(sA0, sA1);
.LBB0_733:
	v_lshlrev_b32_e32 v0, 4, v4
	v_mul_u32_u24_e32 v2, 0x90, v3
	v_add3_u32 v173, v0, v2, 0
	s_waitcnt vmcnt(0)
	s_waitcnt lgkmcnt(0)
	s_barrier
	ds_read_b128 v[6:9], v173
	ds_read_b128 v[10:13], v173 offset:32
	s_waitcnt vmcnt(3) lgkmcnt(1)
	v_mfma_f32_32x32x16_bf16 v[44:59], v[6:9], v[146:149], 0
	s_cmp_gt_i32 s81, -1
	s_cselect_b64 s[38:39], -1, 0
	s_add_i32 s10, s10, s84
	v_sub_co_u32_e64 v2, s[6:7], s10, 4
	s_nop 0
	v_readfirstlane_b32 s8, v2
	s_min_u32 s1, s8, s1
	s_waitcnt vmcnt(2) lgkmcnt(0)
	v_mfma_f32_32x32x16_bf16 v[44:59], v[10:13], v[150:153], v[44:59]
	ds_read_b128 v[6:9], v173 offset:4608
	ds_read_b128 v[10:13], v173 offset:4640
	s_and_b64 s[6:7], s[6:7], exec
	s_cselect_b32 s33, 0, s1
	s_cmp_ge_u32 s79, s33
	s_cselect_b64 s[6:7], -1, 0
	s_add_i32 s88, s33, 8
	v_readlane_b32 s1, v244, 28
	s_waitcnt lgkmcnt(1)
	v_mfma_f32_32x32x16_bf16 v[28:43], v[6:9], v[146:149], 0
	s_cmp_lt_u32 s79, s88
	v_or_b32_e32 v5, s1, v3
	s_cselect_b64 s[8:9], -1, 0
	s_sub_i32 s1, s79, s10
	s_and_b64 s[6:7], s[6:7], s[8:9]
	s_mul_i32 s1, s1, 31
	s_addk_i32 s1, 0xe8
	s_waitcnt lgkmcnt(0)
	v_mfma_f32_32x32x16_bf16 v[28:43], v[10:13], v[150:153], v[28:43]
	ds_read_b128 v[6:9], v173 offset:64
	ds_read_b128 v[10:13], v173 offset:96
	s_and_b64 vcc, s[38:39], s[6:7]
	s_and_b64 s[6:7], vcc, exec
	s_cselect_b32 s1, s1, 15
	v_med3_u32 v2, v5, 8, 56
	v_sub_u32_e32 v5, s1, v5
	v_lshlrev_b32_e32 v5, 2, v5
	s_waitcnt vmcnt(1) lgkmcnt(1)
	v_mfma_f32_32x32x16_bf16 v[44:59], v[6:9], v[154:157], v[44:59]
	ds_read_b128 v[6:9], v173 offset:4672
	ds_read_b128 v[14:17], v173 offset:4704
	s_add_i32 s1, 0, 0x16400
	v_lshlrev_b32_e32 v172, 2, v4
	v_sub_u32_e32 v2, v172, v2
	v_add_u32_e32 v2, 8, v2
	v_cndmask_b32_e32 v4, v176, v2, vcc
	v_cmp_gt_u32_e32 vcc, 16, v4
	s_waitcnt lgkmcnt(1)
	v_mfma_f32_32x32x16_bf16 v[28:43], v[6:9], v[154:157], v[28:43]
	v_add3_u32 v6, s1, v5, v0
	ds_read_b32 v5, v6 offset:128
	s_waitcnt vmcnt(0)
	v_mfma_f32_32x32x16_bf16 v[44:59], v[10:13], v[158:161], v[44:59]
	s_waitcnt lgkmcnt(1)
	v_mfma_f32_32x32x16_bf16 v[28:43], v[14:17], v[158:161], v[28:43]
	v_mov_b32_e32 v17, 0xff800000
	v_mov_b32_e32 v16, 0xff800000
	ds_read_b32 v16, v6
	ds_read_b32 v17, v6 offset:4
	ds_read_b32 v18, v6 offset:8
	ds_read_b32 v19, v6 offset:12
	ds_read_b32 v20, v6 offset:32
	ds_read_b32 v21, v6 offset:36
	ds_read_b32 v22, v6 offset:40
	ds_read_b32 v23, v6 offset:44
	ds_read_b32 v24, v6 offset:64
	ds_read_b32 v25, v6 offset:68
	ds_read_b32 v26, v6 offset:72
	ds_read_b32 v27, v6 offset:76
	ds_read_b32 v60, v6 offset:96
	ds_read_b32 v61, v6 offset:100
	ds_read_b32 v62, v6 offset:104
	ds_read_b32 v63, v6 offset:108
	s_waitcnt lgkmcnt(0)
	v_cmp_gt_u32_e32 vcc, 16, v4
	v_add_f32_e32 v16, v44, v16
	v_add_u32_e32 v207, 1, v4
	v_cndmask_b32_e32 v16, v177, v16, vcc
	v_cmp_gt_u32_e32 vcc, 16, v207
	v_add_f32_e32 v17, v45, v17
	v_add_u32_e32 v207, 2, v4
	v_cndmask_b32_e32 v17, v177, v17, vcc
	v_cmp_gt_u32_e32 vcc, 16, v207
	v_add_f32_e32 v18, v46, v18
	v_add_u32_e32 v207, 3, v4
	v_cndmask_b32_e32 v18, v177, v18, vcc
	v_cmp_gt_u32_e32 vcc, 16, v207
	v_add_f32_e32 v19, v47, v19
	v_add_u32_e32 v207, 8, v4
	v_cndmask_b32_e32 v19, v177, v19, vcc
	v_cmp_gt_u32_e32 vcc, 16, v207
	v_add_f32_e32 v20, v48, v20
	v_add_u32_e32 v207, 9, v4
	v_cndmask_b32_e32 v20, v177, v20, vcc
	v_cmp_gt_u32_e32 vcc, 16, v207
	v_add_f32_e32 v21, v49, v21
	v_add_u32_e32 v207, 10, v4
	v_cndmask_b32_e32 v21, v177, v21, vcc
	v_cmp_gt_u32_e32 vcc, 16, v207
	v_add_f32_e32 v22, v50, v22
	v_add_u32_e32 v207, 11, v4
	v_cndmask_b32_e32 v22, v177, v22, vcc
	v_cmp_gt_u32_e32 vcc, 16, v207
	v_add_f32_e32 v23, v51, v23
	s_nop 0
	v_cndmask_b32_e32 v23, v177, v23, vcc
	v_cmp_lt_u32_e32 vcc, s40, v4
	v_add_f32_e32 v24, v52, v24
	v_add_u32_e32 v207, 17, v4
	v_cndmask_b32_e32 v24, v177, v24, vcc
	v_cmp_gt_u32_e32 vcc, 16, v207
	v_add_f32_e32 v25, v53, v25
	v_add_u32_e32 v207, 18, v4
	v_cndmask_b32_e32 v25, v177, v25, vcc
	v_cmp_gt_u32_e32 vcc, 16, v207
	v_add_f32_e32 v26, v54, v26
	v_add_u32_e32 v207, 19, v4
	v_cndmask_b32_e32 v26, v177, v26, vcc
	v_cmp_gt_u32_e32 vcc, 16, v207
	v_add_f32_e32 v27, v55, v27
	v_add_u32_e32 v207, 24, v4
	v_cndmask_b32_e32 v27, v177, v27, vcc
	v_cmp_gt_u32_e32 vcc, 16, v207
	v_add_f32_e32 v60, v56, v60
	v_add_u32_e32 v207, 25, v4
	v_cndmask_b32_e32 v60, v177, v60, vcc
	v_cmp_gt_u32_e32 vcc, 16, v207
	v_add_f32_e32 v61, v57, v61
	v_add_u32_e32 v207, 26, v4
	v_cndmask_b32_e32 v61, v177, v61, vcc
	v_cmp_gt_u32_e32 vcc, 16, v207
	v_add_f32_e32 v62, v58, v62
	v_add_u32_e32 v207, 27, v4
	v_cndmask_b32_e32 v62, v177, v62, vcc
	v_cmp_gt_u32_e32 vcc, 16, v207
	v_add_f32_e32 v63, v59, v63
	s_nop 0
	v_cndmask_b32_e32 v63, v177, v63, vcc
	ds_read_b32 v7, v6 offset:132
	ds_read_b32 v8, v6 offset:136
	ds_read_b32 v9, v6 offset:140
	ds_read_b32 v10, v6 offset:160
	ds_read_b32 v11, v6 offset:164
	ds_read_b32 v12, v6 offset:168
	ds_read_b32 v13, v6 offset:172
	ds_read_b32 v14, v6 offset:192
	ds_read_b32 v15, v6 offset:196
	ds_read_b32 v44, v6 offset:200
	ds_read_b32 v45, v6 offset:204
	ds_read_b32 v46, v6 offset:224
	ds_read_b32 v47, v6 offset:228
	ds_read_b32 v48, v6 offset:232
	ds_read_b32 v49, v6 offset:236
	s_waitcnt lgkmcnt(14)
	v_add_f32_e32 v6, v29, v7
	s_waitcnt lgkmcnt(13)
	v_add_f32_e32 v7, v30, v8
	s_waitcnt lgkmcnt(12)
	v_add_f32_e32 v8, v31, v9
	s_waitcnt lgkmcnt(11)
	v_add_f32_e32 v9, v32, v10
	s_waitcnt lgkmcnt(10)
; __device__ __forceinline__ float max3f(float a, float b, float c) { float r; asm("v_max3_f32 %0, %1, %2, %3" : "=v"(r) : "v"(a), "v"(b), "v"(c)); return r; }
; __device__ __forceinline__ float rowmax32(const f32x16& p0, const f32x16& p1) {
;     float a = max3f(p0[0], p0[1], p1[0]), b = max3f(p0[2], p0[3], p1[1]); a = max3f(a, p1[2], p1[3]);
; #pragma unroll
;     for (int r = 4; r < 16; r += 4) { a = max3f(a, p0[r], p0[r + 1]); b = max3f(b, p0[r + 2], p0[r + 3]); a = max3f(a, p1[r], p1[r + 1]); b = max3f(b, p1[r + 2], p1[r + 3]); }
;     const float m = fmaxf(a, b);
;     auto rr = __builtin_amdgcn_permlane32_swap(__float_as_uint(m), __float_as_uint(m), false, false);
;     return fmaxf(__uint_as_float(rr[0]), __uint_as_float(rr[1]));
; }
	v_add_f32_e32 v10, v33, v11
	v_add_u32_e32 v33, 33, v4
	v_cmp_gt_u32_e32 vcc, 16, v33
	v_add_u32_e32 v33, 34, v4
	v_cmp_gt_u32_e64 s[6:7], 16, v33
	v_add_u32_e32 v33, 35, v4
	v_cmp_gt_u32_e64 s[8:9], 16, v33
	v_add_u32_e32 v33, 40, v4
	v_cmp_gt_u32_e64 s[10:11], 16, v33
	v_add_u32_e32 v33, 41, v4
	v_cmp_gt_u32_e64 s[12:13], 16, v33
	v_add_u32_e32 v33, 42, v4
	v_cmp_gt_u32_e64 s[14:15], 16, v33
	v_add_u32_e32 v33, 43, v4
	v_cmp_gt_u32_e64 s[16:17], 16, v33
	v_add_u32_e32 v33, 49, v4
	v_cmp_gt_u32_e64 s[18:19], 16, v33
	v_add_u32_e32 v33, 50, v4
	v_cmp_gt_u32_e64 s[20:21], 16, v33
	v_add_u32_e32 v33, 51, v4
	v_cmp_gt_u32_e64 s[22:23], 16, v33
	v_add_u32_e32 v33, 56, v4
	v_cmp_gt_u32_e64 s[24:25], 16, v33
	v_add_u32_e32 v33, 57, v4
	v_cmp_gt_u32_e64 s[26:27], 16, v33
	v_add_u32_e32 v33, 58, v4
	v_cmp_gt_u32_e64 s[28:29], 16, v33
	v_add_u32_e32 v33, 59, v4
	v_and_b32_e32 v4, -16, v4
	v_add_f32_e32 v5, v28, v5
	v_cmp_eq_u32_e64 s[36:37], s41, v4
	v_cmp_eq_u32_e64 s[34:35], s42, v4
	v_cndmask_b32_e64 v82, v177, v7, s[6:7]
	v_cndmask_b32_e64 v80, v177, v5, s[36:37]
	v_max3_f32 v4, v16, v17, v80
	v_cndmask_b32_e64 v81, v177, v8, s[8:9]
	v_max3_f32 v4, v4, v82, v81
	v_cndmask_b32_e32 v95, v177, v6, vcc
	v_max3_f32 v5, v18, v19, v95
	s_waitcnt lgkmcnt(9)
	v_add_f32_e32 v11, v34, v12
	s_waitcnt lgkmcnt(8)
	v_add_f32_e32 v12, v35, v13
	v_max3_f32 v4, v4, v20, v21
	v_max3_f32 v5, v5, v22, v23
	v_cndmask_b32_e64 v84, v177, v9, s[10:11]
	v_cndmask_b32_e64 v89, v177, v10, s[12:13]
	v_max3_f32 v4, v4, v84, v89
	v_cndmask_b32_e64 v86, v177, v11, s[14:15]
	v_cndmask_b32_e64 v83, v177, v12, s[16:17]
	v_max3_f32 v5, v5, v86, v83
	s_waitcnt lgkmcnt(7)
	v_add_f32_e32 v13, v36, v14
	s_waitcnt lgkmcnt(6)
	v_add_f32_e32 v14, v37, v15
	s_waitcnt lgkmcnt(5)
	v_add_f32_e32 v15, v38, v44
	s_waitcnt lgkmcnt(4)
	v_add_f32_e32 v28, v39, v45
	v_max3_f32 v4, v4, v24, v25
	v_max3_f32 v5, v5, v26, v27
	v_cndmask_b32_e64 v88, v177, v13, s[34:35]
	v_cndmask_b32_e64 v91, v177, v14, s[18:19]
	v_max3_f32 v4, v4, v88, v91
	v_cndmask_b32_e64 v90, v177, v15, s[20:21]
	v_cndmask_b32_e64 v85, v177, v28, s[22:23]
	v_max3_f32 v5, v5, v90, v85
	s_waitcnt lgkmcnt(3)
	v_add_f32_e32 v29, v40, v46
	s_waitcnt lgkmcnt(2)
	v_add_f32_e32 v30, v41, v47
	s_waitcnt lgkmcnt(1)
	v_add_f32_e32 v31, v42, v48
	s_waitcnt lgkmcnt(0)
	v_add_f32_e32 v32, v43, v49
	v_cmp_gt_u32_e64 s[30:31], 16, v33
	v_max3_f32 v4, v4, v60, v61
	v_max3_f32 v5, v5, v62, v63
	v_cndmask_b32_e64 v92, v177, v29, s[24:25]
	v_cndmask_b32_e64 v93, v177, v30, s[26:27]
	v_max3_f32 v4, v4, v92, v93
	v_cndmask_b32_e64 v94, v177, v31, s[28:29]
	v_cndmask_b32_e64 v87, v177, v32, s[30:31]
	v_max3_f32 v5, v5, v94, v87
	v_max_f32_e32 v4, v4, v4
	v_max_f32_e32 v5, v5, v5
	v_max_f32_e32 v4, v4, v5
	v_mov_b32_e32 v5, v4
	s_nop 1
	v_permlane32_swap_b32_e32 v4, v5
	s_and_b64 vcc, exec, s[38:39]
	s_barrier
	s_cbranch_vccz .LBB0_868
	v_max_f32_e32 v4, v4, v4
	v_max_f32_e32 v5, v5, v5
	v_max_f32_e32 v180, v4, v5
	v_and_b32_e32 v4, -16, v2
	s_movk_i32 s1, 0xffef
	v_cmp_eq_u32_e64 s[8:9], s41, v4
	v_add_u32_e32 v5, 1, v2
	v_cmp_lt_u32_e64 s[40:41], s1, v2
	s_movk_i32 s1, 0xffd0
	v_cmp_gt_u32_e64 s[10:11], 16, v5
	v_add_u32_e32 v5, 33, v2
	v_cmp_eq_u32_e64 s[42:43], s1, v4
	v_add_u32_e32 v4, 17, v2
	v_cmp_gt_u32_e64 s[12:13], 16, v5
	v_add_u32_e32 v5, 2, v2
	v_cmp_gt_u32_e64 s[44:45], 16, v4
	v_add_u32_e32 v4, 49, v2
	v_cmp_gt_u32_e64 s[14:15], 16, v5
	v_add_u32_e32 v5, 34, v2
	v_cmp_gt_u32_e64 s[46:47], 16, v4
	v_add_u32_e32 v4, 18, v2
	v_cmp_gt_u32_e64 s[16:17], 16, v5
	v_add_u32_e32 v5, 3, v2
	v_cmp_gt_u32_e64 s[48:49], 16, v4
	v_add_u32_e32 v4, 50, v2
	v_cmp_gt_u32_e64 s[18:19], 16, v5
	v_add_u32_e32 v5, 35, v2
	v_cmp_gt_u32_e64 s[50:51], 16, v4
	v_add_u32_e32 v4, 19, v2
	v_cmp_gt_u32_e64 s[20:21], 16, v5
	v_add_u32_e32 v5, 8, v2
	v_cmp_gt_u32_e64 s[52:53], 16, v4
	v_add_u32_e32 v4, 51, v2
	v_cmp_gt_u32_e64 s[22:23], 16, v5
	v_add_u32_e32 v5, 40, v2
	v_cmp_gt_u32_e64 s[54:55], 16, v4
	v_add_u32_e32 v4, 24, v2
	v_cmp_gt_u32_e64 s[24:25], 16, v5
	v_add_u32_e32 v5, 9, v2
	v_cmp_gt_u32_e64 s[56:57], 16, v4
	v_add_u32_e32 v4, 56, v2
	v_cmp_gt_u32_e64 s[26:27], 16, v5
	v_add_u32_e32 v5, 41, v2
	v_cmp_gt_u32_e64 s[58:59], 16, v4
	v_add_u32_e32 v4, 25, v2
	v_cmp_gt_u32_e64 s[28:29], 16, v5
	v_add_u32_e32 v5, 10, v2
	v_cmp_gt_u32_e64 s[60:61], 16, v4
	v_add_u32_e32 v4, 57, v2
	v_cmp_gt_u32_e64 s[30:31], 16, v5
	v_add_u32_e32 v5, 42, v2
	v_cmp_gt_u32_e64 s[62:63], 16, v4
	v_add_u32_e32 v4, 26, v2
	v_cmp_gt_u32_e64 s[34:35], 16, v5
	v_add_u32_e32 v5, 11, v2
	v_cmp_gt_u32_e64 s[64:65], 16, v4
	v_add_u32_e32 v4, 58, v2
	v_cmp_gt_u32_e64 s[6:7], 16, v2
	v_cmp_gt_u32_e64 s[36:37], 16, v5
	v_add_u32_e32 v5, 43, v2
	v_cmp_gt_u32_e64 s[66:67], 16, v4
	v_add_u32_e32 v4, 27, v2
	v_add_u32_e32 v2, 59, v2
	s_mul_i32 s1, s79, 0x7c
	v_cmp_gt_u32_e64 s[70:71], 16, v2
	v_add_u32_e32 v0, s1, v0
	v_lshlrev_b32_e32 v2, 2, v3
	v_sub_u32_e32 v0, v0, v2
	s_mulk_i32 s0, 0x1f0
	v_subrev_u32_e32 v0, s0, v0
	v_readlane_b32 s0, v244, 29
	v_mov_b32_e32 v14, v1
	v_mov_b32_e32 v15, v1
	v_cmp_gt_u32_e64 s[38:39], 16, v5
	v_cmp_gt_u32_e64 s[68:69], 16, v4
	v_add_u32_e32 v179, s0, v0
	v_mov_b32_e32 v0, v1
	v_mov_b32_e32 v2, v1
	v_mov_b32_e32 v3, v1
	v_mov_b32_e32 v4, v1
	v_mov_b32_e32 v5, v1
	v_mov_b32_e32 v6, v1
	v_mov_b32_e32 v7, v1
	v_mov_b32_e32 v8, v1
	v_mov_b32_e32 v9, v1
	v_mov_b32_e32 v10, v1
	v_mov_b32_e32 v11, v1
	v_mov_b32_e32 v12, v1
	v_mov_b32_e32 v13, v1
	v_mov_b32_e32 v178, 0
	v_mov_b64_e32 v[58:59], v[14:15]
	v_mov_b64_e32 v[42:43], v[14:15]
	s_sub_i32 s83, s79, s33
	s_mov_b32 s1, 4
	v_mov_b64_e32 v[56:57], v[12:13]
	v_mov_b64_e32 v[54:55], v[10:11]
	v_mov_b64_e32 v[52:53], v[8:9]
	v_mov_b64_e32 v[50:51], v[6:7]
	v_mov_b64_e32 v[48:49], v[4:5]
	v_mov_b64_e32 v[46:47], v[2:3]
	v_mov_b64_e32 v[44:45], v[0:1]
	v_mov_b64_e32 v[40:41], v[12:13]
	v_mov_b64_e32 v[38:39], v[10:11]
	v_mov_b64_e32 v[36:37], v[8:9]
	v_mov_b64_e32 v[34:35], v[6:7]
	v_mov_b64_e32 v[32:33], v[4:5]
	v_mov_b64_e32 v[30:31], v[2:3]
	v_mov_b64_e32 v[28:29], v[0:1]
	v_mov_b32_e32 v2, 0
	v_mov_b32_e32 v112, 0
	v_mov_b32_e32 v113, v178
	v_mov_b32_e32 v114, v178
	v_mov_b32_e32 v115, v178
	v_mov_b32_e32 v116, v178
	v_mov_b32_e32 v117, v178
	v_mov_b32_e32 v118, v178
	v_mov_b32_e32 v119, v178
	v_mov_b32_e32 v120, v178
	v_mov_b32_e32 v121, v178
	v_mov_b32_e32 v122, v178
	v_mov_b32_e32 v123, v178
	v_mov_b32_e32 v124, v178
	v_mov_b32_e32 v125, v178
	v_mov_b32_e32 v126, v178
	v_mov_b32_e32 v127, v178
	s_branch .LBB0_768
